# P4 A-out epilogue de-serialised: second half's residual x loads issued right after the first half's into free registers (v214-v255), copies at the old load site, counted waits adjusted
# baseline (speedup 1.0000x reference)
.LBB0_560:
	v_lshl_or_b32 v130, s10, 8, v189
	v_lshl_add_u32 v174, s12, 8, v1
	v_ashrrev_i32_e32 v131, 31, v130
	v_lshlrev_b64 v[170:171], 1, v[130:131]
	v_ashrrev_i32_e32 v175, 31, v174
	v_lshl_add_u64 v[172:173], s[24:25], 0, v[170:171]
	v_lshlrev_b64 v[204:205], 11, v[174:175]
	v_lshl_add_u64 v[130:131], v[172:173], 0, v[204:205]
	global_load_dwordx4 v[194:197], v[130:131], off nt
	global_load_dwordx4 v[200:203], v[130:131], off offset:256 nt
	v_or_b32_e32 v184, 16, v174
	v_or_b32_e32 v180, 32, v174
	v_or_b32_e32 v176, 48, v174
	v_ashrrev_i32_e32 v185, 31, v184
	v_ashrrev_i32_e32 v181, 31, v180
	v_ashrrev_i32_e32 v177, 31, v176
	v_lshlrev_b64 v[186:187], 11, v[184:185]
	v_lshlrev_b64 v[182:183], 11, v[180:181]
	v_lshlrev_b64 v[178:179], 11, v[176:177]
	v_lshl_add_u64 v[130:131], v[172:173], 0, v[186:187]
	v_lshl_add_u64 v[132:133], v[172:173], 0, v[182:183]
	v_lshl_add_u64 v[206:207], v[172:173], 0, v[178:179]
	global_load_dwordx4 v[150:153], v[130:131], off nt
	global_load_dwordx4 v[146:149], v[130:131], off offset:256 nt
	global_load_dwordx4 v[142:145], v[132:133], off nt
	global_load_dwordx4 v[138:141], v[132:133], off offset:256 nt
	global_load_dwordx4 v[134:137], v[206:207], off nt
	s_nop 0
	global_load_dwordx4 v[130:133], v[206:207], off offset:256 nt
	v_add_u32_e32 v222, 0x80, v174
	v_ashrrev_i32_e32 v223, 31, v222
	v_lshlrev_b64 v[214:215], 11, v[222:223]
	v_lshl_add_u64 v[214:215], v[172:173], 0, v[214:215]
	global_load_dwordx4 v[228:231], v[214:215], off nt
	global_load_dwordx4 v[232:235], v[214:215], off offset:256 nt
	v_add_u32_e32 v222, 0x90, v174
	v_ashrrev_i32_e32 v223, 31, v222
	v_lshlrev_b64 v[216:217], 11, v[222:223]
	v_lshl_add_u64 v[216:217], v[172:173], 0, v[216:217]
	global_load_dwordx4 v[236:239], v[216:217], off nt
	global_load_dwordx4 v[240:243], v[216:217], off offset:256 nt
	v_add_u32_e32 v222, 0xa0, v174
	v_ashrrev_i32_e32 v223, 31, v222
	v_lshlrev_b64 v[218:219], 11, v[222:223]
	v_lshl_add_u64 v[218:219], v[172:173], 0, v[218:219]
	global_load_dwordx4 v[244:247], v[218:219], off nt
	global_load_dwordx4 v[248:251], v[218:219], off offset:256 nt
	v_add_u32_e32 v222, 0xb0, v174
	v_ashrrev_i32_e32 v223, 31, v222
	v_lshlrev_b64 v[220:221], 11, v[222:223]
	v_lshl_add_u64 v[220:221], v[172:173], 0, v[220:221]
	global_load_dwordx4 v[252:255], v[220:221], off nt
	global_load_dwordx4 v[224:227], v[220:221], off offset:256 nt
	v_lshl_add_u64 v[170:171], s[22:23], 0, v[170:171]
	v_lshl_add_u64 v[204:205], v[170:171], 0, v[204:205]
	s_waitcnt vmcnt(8)
	v_lshlrev_b32_e32 v206, 16, v194
	v_and_b32_e32 v207, 0xffff0000, v194
	v_lshlrev_b32_e32 v194, 16, v195
	v_and_b32_e32 v195, 0xffff0000, v195
	v_lshlrev_b32_e32 v208, 16, v196
	v_and_b32_e32 v209, 0xffff0000, v196
	v_lshlrev_b32_e32 v196, 16, v197
	v_and_b32_e32 v197, 0xffff0000, v197
	v_lshlrev_b32_e32 v210, 16, v200
	v_and_b32_e32 v211, 0xffff0000, v200
	v_lshlrev_b32_e32 v200, 16, v201
	v_and_b32_e32 v201, 0xffff0000, v201
	v_lshlrev_b32_e32 v212, 16, v202
	v_and_b32_e32 v213, 0xffff0000, v202
	v_lshlrev_b32_e32 v202, 16, v203
	v_and_b32_e32 v203, 0xffff0000, v203
	v_pk_add_f32 v[128:129], v[128:129], v[194:195]
	v_pk_add_f32 v[126:127], v[126:127], v[206:207]
	v_pk_add_f32 v[124:125], v[124:125], v[196:197]
	v_pk_add_f32 v[122:123], v[122:123], v[208:209]
	v_pk_add_f32 v[120:121], v[120:121], v[200:201]
	v_pk_add_f32 v[118:119], v[118:119], v[210:211]
	v_pk_add_f32 v[194:195], v[116:117], v[202:203]
	v_pk_add_f32 v[196:197], v[114:115], v[212:213]
	v_mul_f32_e32 v193, v127, v127
	v_mul_f32_e32 v199, v129, v129
	v_mul_f32_e32 v200, v123, v123
	v_mul_f32_e32 v201, v125, v125
	v_cvt_pk_bf16_f32 v114, v126, v127
	v_cvt_pk_bf16_f32 v115, v128, v129
	v_cvt_pk_bf16_f32 v116, v122, v123
	v_cvt_pk_bf16_f32 v117, v124, v125
	v_mul_f32_e32 v123, v119, v119
	v_mul_f32_e32 v125, v121, v121
	v_mul_f32_e32 v127, v197, v197
	v_mul_f32_e32 v129, v195, v195
	v_fmac_f32_e32 v193, v126, v126
	v_fmac_f32_e32 v199, v128, v128
	v_fmac_f32_e32 v200, v122, v122
	v_fmac_f32_e32 v201, v124, v124
	v_fmac_f32_e32 v123, v118, v118
	v_fmac_f32_e32 v125, v120, v120
	v_fmac_f32_e32 v127, v196, v196
	v_fmac_f32_e32 v129, v194, v194
	global_store_dwordx4 v[204:205], v[114:117], off
	s_nop 1
	v_cvt_pk_bf16_f32 v114, v118, v119
	v_cvt_pk_bf16_f32 v115, v120, v121
	v_add_f32_e32 v118, v193, v199
	v_add_f32_e32 v119, v200, v201
	v_add_f32_e32 v120, v123, v125
	v_add_f32_e32 v121, v127, v129
	v_cvt_pk_bf16_f32 v116, v196, v197
	v_cvt_pk_bf16_f32 v117, v194, v195
	global_store_dwordx4 v[204:205], v[114:117], off offset:256
	s_nop 1
	v_add_f32_e32 v114, v118, v119
	v_add_f32_e32 v115, v120, v121
	v_add_f32_e32 v114, v114, v115
	v_mov_b32_e32 v115, v114
	s_nop 1
	v_permlane16_swap_b32_e32 v114, v115
	v_add_f32_e32 v114, v114, v115
	v_mov_b32_e32 v115, v114
	s_nop 1
	v_permlane32_swap_b32_e32 v114, v115
	s_and_saveexec_b64 s[52:53], s[4:5]
	s_cbranch_execz .LBB0_562
	v_add_f32_e32 v116, v114, v115
	s_lshl_b32 s54, s10, 2
	v_lshlrev_b64 v[114:115], 6, v[174:175]
	s_ashr_i32 s55, s54, 31
	v_lshl_add_u64 v[114:115], s[26:27], 0, v[114:115]
	v_lshl_add_u64 v[114:115], s[54:55], 2, v[114:115]
	s_lshl_b32 s12, s66, 2
	v_lshl_add_u64 v[114:115], v[114:115], 0, s[12:13]
	global_store_dword v[114:115], v116, off

.LBB0_568:
	s_or_b64 exec, exec, s[52:53]
	v_add_u32_e32 v100, 0x80, v174
	v_ashrrev_i32_e32 v101, 31, v100
	v_lshlrev_b64 v[112:113], 11, v[100:101]
	v_lshl_add_u64 v[66:67], v[172:173], 0, v[112:113]
	s_waitcnt vmcnt(8)
	v_mov_b32_e32 v104, v228
	v_mov_b32_e32 v105, v229
	v_mov_b32_e32 v106, v230
	v_mov_b32_e32 v107, v231
	v_mov_b32_e32 v108, v232
	v_mov_b32_e32 v109, v233
	v_mov_b32_e32 v110, v234
	v_mov_b32_e32 v111, v235
	v_add_u32_e32 v98, 0x90, v174
	v_add_u32_e32 v94, 0xa0, v174
	v_add_u32_e32 v90, 0xb0, v174
	v_ashrrev_i32_e32 v99, 31, v98
	v_ashrrev_i32_e32 v95, 31, v94
	v_ashrrev_i32_e32 v91, 31, v90
	v_lshlrev_b64 v[102:103], 11, v[98:99]
	v_lshlrev_b64 v[96:97], 11, v[94:95]
	v_lshlrev_b64 v[92:93], 11, v[90:91]
	v_lshl_add_u64 v[66:67], v[172:173], 0, v[102:103]
	v_lshl_add_u64 v[68:69], v[172:173], 0, v[96:97]
	v_lshl_add_u64 v[114:115], v[172:173], 0, v[92:93]
	v_mov_b32_e32 v86, v236
	v_mov_b32_e32 v87, v237
	v_mov_b32_e32 v88, v238
	v_mov_b32_e32 v89, v239
	v_mov_b32_e32 v82, v240
	v_mov_b32_e32 v83, v241
	v_mov_b32_e32 v84, v242
	v_mov_b32_e32 v85, v243
	v_mov_b32_e32 v78, v244
	v_mov_b32_e32 v79, v245
	v_mov_b32_e32 v80, v246
	v_mov_b32_e32 v81, v247
	v_mov_b32_e32 v74, v248
	v_mov_b32_e32 v75, v249
	v_mov_b32_e32 v76, v250
	v_mov_b32_e32 v77, v251
	v_mov_b32_e32 v70, v252
	v_mov_b32_e32 v71, v253
	v_mov_b32_e32 v72, v254
	v_mov_b32_e32 v73, v255
	s_nop 0
	v_mov_b32_e32 v66, v224
	v_mov_b32_e32 v67, v225
	v_mov_b32_e32 v68, v226
	v_mov_b32_e32 v69, v227
	v_lshl_add_u64 v[112:113], v[170:171], 0, v[112:113]
	v_lshlrev_b32_e32 v114, 16, v104
	v_and_b32_e32 v115, 0xffff0000, v104
	v_lshlrev_b32_e32 v104, 16, v105
	v_and_b32_e32 v105, 0xffff0000, v105
	v_lshlrev_b32_e32 v116, 16, v106
	v_and_b32_e32 v117, 0xffff0000, v106
	v_lshlrev_b32_e32 v106, 16, v107
	v_and_b32_e32 v107, 0xffff0000, v107
	v_lshlrev_b32_e32 v118, 16, v108
	v_and_b32_e32 v119, 0xffff0000, v108
	v_lshlrev_b32_e32 v108, 16, v109
	v_and_b32_e32 v109, 0xffff0000, v109
	v_lshlrev_b32_e32 v120, 16, v110
	v_and_b32_e32 v121, 0xffff0000, v110
	v_lshlrev_b32_e32 v110, 16, v111
	v_and_b32_e32 v111, 0xffff0000, v111
	v_pk_add_f32 v[64:65], v[64:65], v[104:105]
	v_pk_add_f32 v[62:63], v[62:63], v[114:115]
	v_pk_add_f32 v[60:61], v[60:61], v[106:107]
	v_pk_add_f32 v[58:59], v[58:59], v[116:117]
	v_pk_add_f32 v[56:57], v[56:57], v[108:109]
	v_pk_add_f32 v[54:55], v[54:55], v[118:119]
	v_pk_add_f32 v[104:105], v[52:53], v[110:111]
	v_pk_add_f32 v[106:107], v[50:51], v[120:121]
	v_mul_f32_e32 v108, v63, v63
	v_mul_f32_e32 v109, v65, v65
	v_mul_f32_e32 v110, v59, v59
	v_mul_f32_e32 v111, v61, v61
	v_cvt_pk_bf16_f32 v50, v62, v63
	v_cvt_pk_bf16_f32 v51, v64, v65
	v_cvt_pk_bf16_f32 v52, v58, v59
	v_cvt_pk_bf16_f32 v53, v60, v61
	v_mul_f32_e32 v59, v55, v55
	v_mul_f32_e32 v61, v57, v57
	v_mul_f32_e32 v63, v107, v107
	v_mul_f32_e32 v65, v105, v105
	v_fmac_f32_e32 v108, v62, v62
	v_fmac_f32_e32 v109, v64, v64
	v_fmac_f32_e32 v110, v58, v58
	v_fmac_f32_e32 v111, v60, v60
	v_fmac_f32_e32 v59, v54, v54
	v_fmac_f32_e32 v61, v56, v56
	v_fmac_f32_e32 v63, v106, v106
	v_fmac_f32_e32 v65, v104, v104
	global_store_dwordx4 v[112:113], v[50:53], off
	s_nop 1
	v_cvt_pk_bf16_f32 v50, v54, v55
	v_cvt_pk_bf16_f32 v51, v56, v57
	v_add_f32_e32 v54, v108, v109
	v_add_f32_e32 v55, v110, v111
	v_add_f32_e32 v56, v59, v61
	v_add_f32_e32 v57, v63, v65
	v_cvt_pk_bf16_f32 v52, v106, v107
	v_cvt_pk_bf16_f32 v53, v104, v105
	global_store_dwordx4 v[112:113], v[50:53], off offset:256
	s_nop 1
	v_add_f32_e32 v50, v54, v55
	v_add_f32_e32 v51, v56, v57
	v_add_f32_e32 v50, v50, v51
	v_mov_b32_e32 v51, v50
	s_nop 1
	v_permlane16_swap_b32_e32 v50, v51
	v_add_f32_e32 v50, v50, v51
	v_mov_b32_e32 v51, v50
	s_nop 1
	v_permlane32_swap_b32_e32 v50, v51
	s_and_saveexec_b64 s[52:53], s[4:5]
	s_cbranch_execz .LBB0_570
	v_add_f32_e32 v52, v50, v51
	s_lshl_b32 s54, s10, 2
	v_lshlrev_b64 v[50:51], 6, v[100:101]
	s_ashr_i32 s55, s54, 31
	v_lshl_add_u64 v[50:51], s[26:27], 0, v[50:51]
	v_lshl_add_u64 v[50:51], s[54:55], 2, v[50:51]
	s_lshl_b32 s12, s66, 2
	v_lshl_add_u64 v[50:51], v[50:51], 0, s[12:13]
	global_store_dword v[50:51], v52, off
.LBB0_570:
	s_or_b64 exec, exec, s[52:53]
	v_lshlrev_b32_e32 v50, 16, v86
	v_and_b32_e32 v51, 0xffff0000, v86
	v_lshlrev_b32_e32 v52, 16, v87
	v_and_b32_e32 v53, 0xffff0000, v87
	v_lshlrev_b32_e32 v54, 16, v88
	v_and_b32_e32 v55, 0xffff0000, v88
	v_lshlrev_b32_e32 v56, 16, v89
	v_and_b32_e32 v57, 0xffff0000, v89
	v_pk_add_f32 v[48:49], v[48:49], v[52:53]
	v_pk_add_f32 v[46:47], v[46:47], v[50:51]
	v_pk_add_f32 v[50:51], v[44:45], v[56:57]
	v_pk_add_f32 v[44:45], v[42:43], v[54:55]
	v_mul_f32_e32 v42, v47, v47
	v_mul_f32_e32 v43, v49, v49
	v_fmac_f32_e32 v42, v46, v46
	v_fmac_f32_e32 v43, v48, v48
	v_add_f32_e32 v42, v42, v43
	v_mul_f32_e32 v43, v45, v45
	v_mul_f32_e32 v52, v51, v51
	v_fmac_f32_e32 v43, v44, v44
	v_fmac_f32_e32 v52, v50, v50
	v_lshlrev_b32_e32 v58, 16, v82
	v_and_b32_e32 v59, 0xffff0000, v82
	v_lshlrev_b32_e32 v60, 16, v83
	v_and_b32_e32 v61, 0xffff0000, v83
	v_add_f32_e32 v43, v43, v52
	v_lshlrev_b32_e32 v62, 16, v84
	v_and_b32_e32 v63, 0xffff0000, v84
	v_lshlrev_b32_e32 v64, 16, v85
	v_and_b32_e32 v65, 0xffff0000, v85
	v_lshl_add_u64 v[82:83], v[170:171], 0, v[102:103]
	v_add_f32_e32 v52, v42, v43
	v_cvt_pk_bf16_f32 v42, v46, v47
	v_cvt_pk_bf16_f32 v43, v48, v49
	v_pk_add_f32 v[40:41], v[40:41], v[60:61]
	v_pk_add_f32 v[38:39], v[38:39], v[58:59]
	v_cvt_pk_bf16_f32 v44, v44, v45
	v_cvt_pk_bf16_f32 v45, v50, v51
	global_store_dwordx4 v[82:83], v[42:45], off
	s_nop 1
	v_pk_add_f32 v[42:43], v[36:37], v[64:65]
	v_pk_add_f32 v[36:37], v[34:35], v[62:63]
	v_mul_f32_e32 v34, v39, v39
	v_mul_f32_e32 v35, v41, v41
	v_fmac_f32_e32 v34, v38, v38
	v_fmac_f32_e32 v35, v40, v40
	v_add_f32_e32 v34, v34, v35
	v_mul_f32_e32 v35, v37, v37
	v_mul_f32_e32 v44, v43, v43
	v_fmac_f32_e32 v35, v36, v36
	v_fmac_f32_e32 v44, v42, v42
	v_add_f32_e32 v35, v35, v44
	v_add_f32_e32 v34, v34, v35
	v_add_f32_e32 v44, v52, v34
	v_cvt_pk_bf16_f32 v34, v38, v39
	v_cvt_pk_bf16_f32 v35, v40, v41
	v_cvt_pk_bf16_f32 v36, v36, v37
	v_cvt_pk_bf16_f32 v37, v42, v43
	global_store_dwordx4 v[82:83], v[34:37], off offset:256
	s_nop 1
	v_mov_b32_e32 v34, v44
	s_nop 1
	v_permlane16_swap_b32_e32 v44, v34
	v_add_f32_e32 v34, v44, v34
	v_mov_b32_e32 v35, v34
	s_nop 1
	v_permlane32_swap_b32_e32 v34, v35
	s_and_saveexec_b64 s[52:53], s[4:5]
	s_cbranch_execz .LBB0_572
	v_add_f32_e32 v36, v34, v35
	s_lshl_b32 s54, s10, 2
	v_lshlrev_b64 v[34:35], 6, v[98:99]
	s_ashr_i32 s55, s54, 31
	v_lshl_add_u64 v[34:35], s[26:27], 0, v[34:35]
	v_lshl_add_u64 v[34:35], s[54:55], 2, v[34:35]
	s_lshl_b32 s12, s66, 2
	v_lshl_add_u64 v[34:35], v[34:35], 0, s[12:13]
	global_store_dword v[34:35], v36, off
.LBB0_572:
	s_or_b64 exec, exec, s[52:53]
	v_lshlrev_b32_e32 v34, 16, v78
	v_and_b32_e32 v35, 0xffff0000, v78
	v_lshlrev_b32_e32 v36, 16, v79
	v_and_b32_e32 v37, 0xffff0000, v79
	v_lshlrev_b32_e32 v38, 16, v80
	v_and_b32_e32 v39, 0xffff0000, v80
	v_lshlrev_b32_e32 v40, 16, v81
	v_and_b32_e32 v41, 0xffff0000, v81
	v_pk_add_f32 v[32:33], v[32:33], v[36:37]
	v_pk_add_f32 v[30:31], v[30:31], v[34:35]
	v_pk_add_f32 v[34:35], v[28:29], v[40:41]
	v_pk_add_f32 v[28:29], v[26:27], v[38:39]
	v_mul_f32_e32 v26, v31, v31
	v_mul_f32_e32 v27, v33, v33
	v_fmac_f32_e32 v26, v30, v30
	v_fmac_f32_e32 v27, v32, v32
	v_add_f32_e32 v26, v26, v27
	v_mul_f32_e32 v27, v29, v29
	v_mul_f32_e32 v36, v35, v35
	v_fmac_f32_e32 v27, v28, v28
	v_fmac_f32_e32 v36, v34, v34
	v_lshlrev_b32_e32 v42, 16, v74
	v_and_b32_e32 v43, 0xffff0000, v74
	v_lshlrev_b32_e32 v44, 16, v75
	v_and_b32_e32 v45, 0xffff0000, v75
	v_add_f32_e32 v27, v27, v36
	v_lshlrev_b32_e32 v46, 16, v76
	v_and_b32_e32 v47, 0xffff0000, v76
	v_lshlrev_b32_e32 v48, 16, v77
	v_and_b32_e32 v49, 0xffff0000, v77
	v_lshl_add_u64 v[50:51], v[170:171], 0, v[96:97]
	v_add_f32_e32 v36, v26, v27
	v_cvt_pk_bf16_f32 v26, v30, v31
	v_cvt_pk_bf16_f32 v27, v32, v33
	v_pk_add_f32 v[24:25], v[24:25], v[44:45]
	v_pk_add_f32 v[22:23], v[22:23], v[42:43]
	v_cvt_pk_bf16_f32 v28, v28, v29
	v_cvt_pk_bf16_f32 v29, v34, v35
	global_store_dwordx4 v[50:51], v[26:29], off
	s_nop 1
	v_pk_add_f32 v[26:27], v[20:21], v[48:49]
	v_pk_add_f32 v[20:21], v[18:19], v[46:47]
	v_mul_f32_e32 v18, v23, v23
	v_mul_f32_e32 v19, v25, v25
	v_fmac_f32_e32 v18, v22, v22
	v_fmac_f32_e32 v19, v24, v24
	v_add_f32_e32 v18, v18, v19
	v_mul_f32_e32 v19, v21, v21
	v_mul_f32_e32 v28, v27, v27
	v_fmac_f32_e32 v19, v20, v20
	v_fmac_f32_e32 v28, v26, v26
	v_add_f32_e32 v19, v19, v28
	v_add_f32_e32 v18, v18, v19
	v_add_f32_e32 v28, v36, v18
	v_cvt_pk_bf16_f32 v18, v22, v23
	v_cvt_pk_bf16_f32 v19, v24, v25
	v_cvt_pk_bf16_f32 v20, v20, v21
	v_cvt_pk_bf16_f32 v21, v26, v27
	global_store_dwordx4 v[50:51], v[18:21], off offset:256
	s_nop 1
	v_mov_b32_e32 v18, v28
	s_nop 1
	v_permlane16_swap_b32_e32 v28, v18
	v_add_f32_e32 v18, v28, v18
	v_mov_b32_e32 v19, v18
	s_nop 1
	v_permlane32_swap_b32_e32 v18, v19
	s_and_saveexec_b64 s[52:53], s[4:5]
	s_cbranch_execz .LBB0_574
	v_add_f32_e32 v20, v18, v19
	s_lshl_b32 s54, s10, 2
	v_lshlrev_b64 v[18:19], 6, v[94:95]
	s_ashr_i32 s55, s54, 31
	v_lshl_add_u64 v[18:19], s[26:27], 0, v[18:19]
	v_lshl_add_u64 v[18:19], s[54:55], 2, v[18:19]
	s_lshl_b32 s12, s66, 2
	v_lshl_add_u64 v[18:19], v[18:19], 0, s[12:13]
	global_store_dword v[18:19], v20, off
.LBB0_574:
	s_or_b64 exec, exec, s[52:53]
	v_lshlrev_b32_e32 v18, 16, v70
	v_and_b32_e32 v19, 0xffff0000, v70
	v_lshlrev_b32_e32 v20, 16, v71
	v_and_b32_e32 v21, 0xffff0000, v71
	v_lshlrev_b32_e32 v22, 16, v72
	v_and_b32_e32 v23, 0xffff0000, v72
	v_lshlrev_b32_e32 v24, 16, v73
	v_and_b32_e32 v25, 0xffff0000, v73
	v_pk_add_f32 v[16:17], v[16:17], v[20:21]
	v_pk_add_f32 v[14:15], v[14:15], v[18:19]
	v_pk_add_f32 v[18:19], v[12:13], v[24:25]
	v_pk_add_f32 v[12:13], v[10:11], v[22:23]
	v_mul_f32_e32 v10, v15, v15
	v_mul_f32_e32 v11, v17, v17
	v_fmac_f32_e32 v10, v14, v14
	v_fmac_f32_e32 v11, v16, v16
	v_add_f32_e32 v10, v10, v11
	v_mul_f32_e32 v11, v13, v13
	v_mul_f32_e32 v20, v19, v19
	v_fmac_f32_e32 v11, v12, v12
	v_fmac_f32_e32 v20, v18, v18
	v_lshlrev_b32_e32 v26, 16, v66
	v_and_b32_e32 v27, 0xffff0000, v66
	v_lshlrev_b32_e32 v28, 16, v67
	v_and_b32_e32 v29, 0xffff0000, v67
	v_add_f32_e32 v11, v11, v20
	v_lshlrev_b32_e32 v30, 16, v68
	v_and_b32_e32 v31, 0xffff0000, v68
	v_lshlrev_b32_e32 v32, 16, v69
	v_and_b32_e32 v33, 0xffff0000, v69
	v_lshl_add_u64 v[34:35], v[170:171], 0, v[92:93]
	v_add_f32_e32 v20, v10, v11
	v_cvt_pk_bf16_f32 v10, v14, v15
	v_cvt_pk_bf16_f32 v11, v16, v17
	v_pk_add_f32 v[8:9], v[8:9], v[28:29]
	v_pk_add_f32 v[6:7], v[6:7], v[26:27]
	v_cvt_pk_bf16_f32 v12, v12, v13
	v_cvt_pk_bf16_f32 v13, v18, v19
	global_store_dwordx4 v[34:35], v[10:13], off
	s_nop 1
	v_pk_add_f32 v[10:11], v[4:5], v[32:33]
	v_pk_add_f32 v[4:5], v[2:3], v[30:31]
	v_mul_f32_e32 v2, v7, v7
	v_mul_f32_e32 v3, v9, v9
	v_fmac_f32_e32 v2, v6, v6
	v_fmac_f32_e32 v3, v8, v8
	v_add_f32_e32 v2, v2, v3
	v_mul_f32_e32 v3, v5, v5
	v_mul_f32_e32 v12, v11, v11
	v_fmac_f32_e32 v3, v4, v4
	v_fmac_f32_e32 v12, v10, v10
	v_add_f32_e32 v3, v3, v12
	v_add_f32_e32 v2, v2, v3
	v_add_f32_e32 v12, v20, v2
	v_cvt_pk_bf16_f32 v2, v6, v7
	v_cvt_pk_bf16_f32 v3, v8, v9
	v_cvt_pk_bf16_f32 v4, v4, v5
	v_cvt_pk_bf16_f32 v5, v10, v11
	global_store_dwordx4 v[34:35], v[2:5], off offset:256
	s_nop 1
	v_mov_b32_e32 v2, v12
	s_nop 1
	v_permlane16_swap_b32_e32 v12, v2
	v_add_f32_e32 v2, v12, v2
	v_mov_b32_e32 v3, v2
	s_nop 1
	v_permlane32_swap_b32_e32 v2, v3
	s_and_saveexec_b64 s[52:53], s[4:5]
	s_cbranch_execz .LBB0_576
	v_add_f32_e32 v4, v2, v3
	s_lshl_b32 s54, s10, 2
	v_lshlrev_b64 v[2:3], 6, v[90:91]
	s_ashr_i32 s55, s54, 31
	v_lshl_add_u64 v[2:3], s[26:27], 0, v[2:3]
	v_lshl_add_u64 v[2:3], s[54:55], 2, v[2:3]
	s_lshl_b32 s12, s66, 2
	v_lshl_add_u64 v[2:3], v[2:3], 0, s[12:13]
	global_store_dword v[2:3], v4, off
